# speedup vs baseline: 1.0061x; 1.0061x over previous
; __global__ void __launch_bounds__(NTHR, 2) hymba_fwd(Args args) {
;     ...
;     for (int ph = lo; ph < hi; ++ph) {
;         int l = ph / NPH; const int k = ph % NPH;
;         if (k == 3 || k == 11) continue;
;         asm volatile("" : "+s"(l));
;         int G = gridDim.x, bid = blockIdx.x; asm volatile("" : "+s"(G), "+s"(bid));
.LBB0_20:
	s_lshr_b32 s5, s54, 1
	s_mul_hi_i32 s0, s5, 0x92492493
	s_add_i32 s0, s0, s5
	s_lshr_b32 s1, s0, 31
	s_ashr_i32 s0, s0, 3
	s_add_i32 s4, s0, s1
	s_mul_i32 s0, s4, 14
	s_sub_i32 s5, s5, s0
	s_cmp_eq_u32 s5, 1
	s_cselect_b32 s0, 1, 0
	s_cmp_eq_u32 s5, 4
	s_cselect_b32 s1, 1, 0
	s_or_b32 s0, s0, s1
	s_cmp_eq_u32 s5, 12
	s_cselect_b32 s1, 1, 0
	s_cmp_eq_u32 s4, 0
	s_cselect_b32 s1, s1, 0
	s_or_b32 s0, s0, s1
	v_readlane_b32 s1, v253, 1
	s_cmp_eq_u32 s1, 0x100
	s_cselect_b32 s0, s0, 0
	s_bitcmp1_b32 s54, 0
	s_cbranch_scc1 .Lhdr_rep1
	s_cmp_eq_u32 s5, 0
	s_cselect_b32 s1, 1, 0
	s_cmp_eq_u32 s4, 1
	s_cselect_b32 s1, s1, 0
	v_readlane_b32 s12, v253, 1
	s_cmp_eq_u32 s12, 0x100
	s_cselect_b32 s1, s1, 0
	s_or_b32 s0, s0, s1
	v_writelane_b32 v255, s0, 62
	s_mov_b32 s0, 0
	s_mov_b32 s1, 0xa07f
	v_writelane_b32 v255, s0, 61
	v_writelane_b32 v255, s1, 59
	s_movk_i32 s0, 0x2c00
	s_cmp_eq_u32 s4, 0
	s_cselect_b32 s0, s0, 0
	s_cmp_eq_u32 s12, 0x100
	s_cselect_b32 s0, s0, 0x7fffffff
	s_mov_b32 s1, 0x9fff
	v_writelane_b32 v255, s0, 57
	v_writelane_b32 v255, s1, 56
	s_branch .Lhdr_common
